# B1: grid barrier one hop shorter - non-leader blocks poll the top-level generation word directly, leader skips XCD generation add
# speedup vs baseline: 1.0068x; 1.0068x over previous
.LBB0_132:
	s_or_b64 exec, exec, s[12:13]
	v_cvt_f32_u32_e32 v4, v2
	s_waitcnt vmcnt(0)
	v_readfirstlane_b32 s3, v3
	v_sub_u32_e32 v3, 0, v2
	s_lshl_b32 s4, s33, 6
	v_rcp_iflag_f32_e32 v4, v4
	v_add_u32_e32 v5, s3, v1
	v_mul_f32_e32 v4, 0x4f7ffffe, v4
	v_cvt_u32_f32_e32 v4, v4
	v_mul_lo_u32 v1, v3, v4
	v_mul_hi_u32 v1, v4, v1
	v_add_u32_e32 v1, v4, v1
	v_mul_hi_u32 v1, v5, v1
	v_mul_lo_u32 v3, v1, v2
	v_sub_u32_e32 v3, v5, v3
	v_add_u32_e32 v4, 1, v1
	v_cmp_ge_u32_e32 vcc, v3, v2
	s_nop 1
	v_cndmask_b32_e32 v1, v1, v4, vcc
	v_sub_u32_e32 v4, v3, v2
	v_cndmask_b32_e32 v3, v3, v4, vcc
	v_add_u32_e32 v4, 1, v1
	v_cmp_ge_u32_e32 vcc, v3, v2
	v_add_u32_e32 v3, 1, v5
	s_nop 0
	v_cndmask_b32_e32 v1, v1, v4, vcc
	v_mul_lo_u32 v4, v2, v1
	v_add_u32_e32 v2, v4, v2
	v_cmp_ne_u32_e32 vcc, v3, v2
	s_and_saveexec_b64 s[10:11], vcc
	s_xor_b64 s[10:11], exec, s[10:11]
	s_cbranch_execz .LBB0_146
	s_waitcnt lgkmcnt(0)
	v_mov_b32_e32 v0, 0
	s_add_u32 s16, s80, 0x7500
	s_addc_u32 s17, s81, 0
	s_nop 0
	global_load_dword v0, v0, s[16:17] sc1
	s_waitcnt vmcnt(0)
	v_cmp_eq_u32_e32 vcc, v0, v1
	s_and_saveexec_b64 s[12:13], vcc
	s_cbranch_execz .LBB0_145
	s_add_u32 s14, s80, 0x4200
	s_addc_u32 s15, s81, 0
	s_mov_b32 s3, 1
	s_mov_b64 s[18:19], 0
	v_mov_b32_e32 v0, 0
	s_branch .LBB0_136

.LBB0_163:
	s_or_b64 exec, exec, s[12:13]
	s_mov_b64 s[12:13], exec
	v_mbcnt_lo_u32_b32 v0, s12, 0
	v_mbcnt_hi_u32_b32 v0, s13, v0
	v_cmp_eq_u32_e32 vcc, 0, v0
	s_waitcnt vmcnt(0)
	buffer_inv sc1
	s_and_saveexec_b64 s[14:15], vcc
	s_cbranch_execz .LBB0_165
	s_bcnt1_i32_b64 s3, s[12:13]
.LBB0_165:
	s_or_b64 exec, exec, s[14:15]
	s_waitcnt vmcnt(0)

.LBB0_168:
	s_or_b64 exec, exec, s[4:5]
	s_waitcnt vmcnt(0)
	buffer_inv sc1
	s_waitcnt vmcnt(0)

.LBB0_603:
	global_atomic_add v4, v[120:121], v160, off sc0
	v_cvt_f32_u32_e32 v0, v3
	v_sub_u32_e32 v5, 0, v3
	v_rcp_iflag_f32_e32 v0, v0
	s_nop 0
	v_mul_f32_e32 v0, 0x4f7ffffe, v0
	v_cvt_u32_f32_e32 v0, v0
	v_mul_lo_u32 v5, v5, v0
	v_mul_hi_u32 v5, v0, v5
	v_add_u32_e32 v0, v0, v5
	s_waitcnt vmcnt(0)
	v_mul_hi_u32 v0, v4, v0
	v_mul_lo_u32 v5, v0, v3
	v_sub_u32_e32 v5, v4, v5
	v_add_u32_e32 v6, 1, v0
	v_cmp_ge_u32_e32 vcc, v5, v3
	v_add_u32_e32 v4, 1, v4
	s_nop 0
	v_cndmask_b32_e32 v0, v0, v6, vcc
	v_sub_u32_e32 v6, v5, v3
	v_cndmask_b32_e32 v5, v5, v6, vcc
	v_add_u32_e32 v6, 1, v0
	v_cmp_ge_u32_e32 vcc, v5, v3
	s_nop 1
	v_cndmask_b32_e32 v0, v0, v6, vcc
	v_mul_lo_u32 v5, v3, v0
	v_add_u32_e32 v3, v5, v3
	v_cmp_ne_u32_e32 vcc, v4, v3
	s_and_saveexec_b64 s[4:5], vcc
	s_xor_b64 s[4:5], exec, s[4:5]
	s_cbranch_execz .LBB0_617
	s_waitcnt lgkmcnt(0)
	v_readlane_b32 s6, v233, 62
	v_readlane_b32 s7, v233, 63
	s_nop 1
	v_mov_b32_e32 v4, s6
	v_mov_b32_e32 v5, s7
	s_nop 0
	global_load_dword v2, v[4:5], off sc1
	s_waitcnt vmcnt(0)
	v_cmp_eq_u32_e32 vcc, v2, v0
	s_and_saveexec_b64 s[6:7], vcc
	s_cbranch_execz .LBB0_616
	s_mov_b32 s22, 1
	s_mov_b64 s[8:9], 0
	s_branch .LBB0_607

.LBB0_611:
	global_load_dword v2, v[4:5], off sc1
	s_add_i32 s22, s22, 1
	s_mov_b64 s[14:15], -1
	s_waitcnt vmcnt(0)
	v_cmp_ne_u32_e32 vcc, v2, v0
	s_orn2_b64 s[12:13], vcc, exec
	s_branch .LBB0_606
